# gate_up K-loop: LDS-DMA loads use scalar base + 32-bit lane offset (no per-piece 64-bit VALU address add)
# speedup vs baseline: 1.0119x; 1.0119x over previous
.LBB0_98:
	s_add_u32 s18, s44, 0xfffc0080
	s_addc_u32 s19, s45, -1
	s_add_i32 s46, 0, 0x10000
	s_cmp_eq_u32 s15, 12
	s_cselect_b32 s25, s7, s19
	s_cselect_b32 s24, s10, s18
	v_add_u32_e32 v148, s46, v150
	s_cselect_b32 s23, s5, s14
	s_cselect_b32 s22, s11, s13
	s_add_i32 s47, 0, 0x14000
	ds_read_b128 v[156:159], v148
	ds_read_b128 v[160:163], v148 offset:1024
	ds_read_b128 v[164:167], v148 offset:2048
	ds_read_b128 v[168:171], v148 offset:3072
	v_add_u32_e32 v148, s47, v150
	ds_read_b128 v[172:175], v148
	ds_read_b128 v[176:179], v148 offset:1024
	ds_read_b128 v[180:183], v148 offset:2048
	ds_read_b128 v[184:187], v148 offset:3072
	s_add_i32 m0, s29, 0xc000
	ds_read_b128 v[208:211], v155
	ds_read_b128 v[212:215], v155 offset:1024
	ds_read_b128 v[216:219], v155 offset:2048
	ds_read_b128 v[220:223], v155 offset:3072
	ds_read_b128 v[224:227], v155 offset:4096
	ds_read_b128 v[228:231], v155 offset:5120
	ds_read_b128 v[232:235], v155 offset:6144
	ds_read_b128 v[236:239], v155 offset:7168
	global_load_lds_dwordx4 v144, s[44:45]
	s_add_i32 m0, s29, 0xe000
	s_nop 0
	global_load_lds_dwordx4 v146, s[44:45]
	s_waitcnt vmcnt(8)
	s_waitcnt lgkmcnt(0)
	s_barrier
	s_setprio 1
	s_waitcnt lgkmcnt(0)
	v_mfma_f32_16x16x32_bf16 v[128:131], v[156:159], v[208:211], v[128:131]
	v_mfma_f32_16x16x32_bf16 v[120:123], v[164:167], v[208:211], v[120:123]
	v_mfma_f32_16x16x32_bf16 v[112:115], v[156:159], v[216:219], v[112:115]
	v_mfma_f32_16x16x32_bf16 v[104:107], v[164:167], v[216:219], v[104:107]
	v_mfma_f32_16x16x32_bf16 v[96:99], v[156:159], v[224:227], v[96:99]
	v_mfma_f32_16x16x32_bf16 v[88:91], v[164:167], v[224:227], v[88:91]
	v_mfma_f32_16x16x32_bf16 v[80:83], v[156:159], v[232:235], v[80:83]
	v_mfma_f32_16x16x32_bf16 v[72:75], v[164:167], v[232:235], v[72:75]
	v_mfma_f32_16x16x32_bf16 v[128:131], v[160:163], v[212:215], v[128:131]
	v_mfma_f32_16x16x32_bf16 v[120:123], v[168:171], v[212:215], v[120:123]
	v_mfma_f32_16x16x32_bf16 v[112:115], v[160:163], v[220:223], v[112:115]
	v_mfma_f32_16x16x32_bf16 v[104:107], v[168:171], v[220:223], v[104:107]
	v_mfma_f32_16x16x32_bf16 v[96:99], v[160:163], v[228:231], v[96:99]
	v_mfma_f32_16x16x32_bf16 v[88:91], v[168:171], v[228:231], v[88:91]
	v_mfma_f32_16x16x32_bf16 v[80:83], v[160:163], v[236:239], v[80:83]
	v_mfma_f32_16x16x32_bf16 v[72:75], v[168:171], v[236:239], v[72:75]
	s_setprio 0
	s_setprio 1
	v_mfma_f32_16x16x32_bf16 v[124:127], v[172:175], v[208:211], v[124:127]
	v_mfma_f32_16x16x32_bf16 v[116:119], v[180:183], v[208:211], v[116:119]
	v_mfma_f32_16x16x32_bf16 v[108:111], v[172:175], v[216:219], v[108:111]
	v_mfma_f32_16x16x32_bf16 v[100:103], v[180:183], v[216:219], v[100:103]
	v_mfma_f32_16x16x32_bf16 v[92:95], v[172:175], v[224:227], v[92:95]
	v_mfma_f32_16x16x32_bf16 v[84:87], v[180:183], v[224:227], v[84:87]
	v_mfma_f32_16x16x32_bf16 v[76:79], v[172:175], v[232:235], v[76:79]
	v_mfma_f32_16x16x32_bf16 v[68:71], v[180:183], v[232:235], v[68:71]
	v_mfma_f32_16x16x32_bf16 v[124:127], v[176:179], v[212:215], v[124:127]
	v_mfma_f32_16x16x32_bf16 v[116:119], v[184:187], v[212:215], v[116:119]
	v_mfma_f32_16x16x32_bf16 v[108:111], v[176:179], v[220:223], v[108:111]
	v_mfma_f32_16x16x32_bf16 v[100:103], v[184:187], v[220:223], v[100:103]
	v_mfma_f32_16x16x32_bf16 v[92:95], v[176:179], v[228:231], v[92:95]
	v_mfma_f32_16x16x32_bf16 v[84:87], v[184:187], v[228:231], v[84:87]
	v_mfma_f32_16x16x32_bf16 v[76:79], v[176:179], v[236:239], v[76:79]
	v_mfma_f32_16x16x32_bf16 v[68:71], v[184:187], v[236:239], v[68:71]
	s_setprio 0
	s_barrier
	s_add_i32 s18, s46, s28
	s_mov_b32 m0, s18
	ds_read_b128 v[208:211], v155 offset:16384
	ds_read_b128 v[212:215], v155 offset:17408
	ds_read_b128 v[216:219], v155 offset:18432
	ds_read_b128 v[220:223], v155 offset:19456
	ds_read_b128 v[224:227], v155 offset:20480
	ds_read_b128 v[228:231], v155 offset:21504
	ds_read_b128 v[232:235], v155 offset:22528
	ds_read_b128 v[236:239], v155 offset:23552
	global_load_lds_dwordx4 v2, s[22:23]
	s_add_i32 m0, s18, 0x2000
	s_add_u32 s18, s22, 0x40000
	s_addc_u32 s19, s23, 0
	s_add_i32 s46, s47, s28
	global_load_lds_dwordx4 v142, s[22:23]
	s_mov_b32 m0, s46
	s_nop 0
	global_load_lds_dwordx4 v2, s[18:19]
	s_add_i32 m0, s46, 0x2000
	s_nop 0
	global_load_lds_dwordx4 v142, s[18:19]
	s_mov_b32 m0, s29
	s_nop 0
	global_load_lds_dwordx4 v0, s[24:25]
	s_mov_b32 m0, s43
	s_nop 0
	global_load_lds_dwordx4 v140, s[24:25]
	s_waitcnt vmcnt(8)
	s_waitcnt lgkmcnt(0)
	s_barrier
	s_setprio 1
	s_waitcnt lgkmcnt(0)
	v_mfma_f32_16x16x32_bf16 v[64:67], v[156:159], v[208:211], v[64:67]
	v_mfma_f32_16x16x32_bf16 v[56:59], v[164:167], v[208:211], v[56:59]
	v_mfma_f32_16x16x32_bf16 v[48:51], v[156:159], v[216:219], v[48:51]
	v_mfma_f32_16x16x32_bf16 v[40:43], v[164:167], v[216:219], v[40:43]
	v_mfma_f32_16x16x32_bf16 v[32:35], v[156:159], v[224:227], v[32:35]
	v_mfma_f32_16x16x32_bf16 v[24:27], v[164:167], v[224:227], v[24:27]
	v_mfma_f32_16x16x32_bf16 v[16:19], v[156:159], v[232:235], v[16:19]
	v_mfma_f32_16x16x32_bf16 v[8:11], v[164:167], v[232:235], v[8:11]
	v_mfma_f32_16x16x32_bf16 v[64:67], v[160:163], v[212:215], v[64:67]
	v_mfma_f32_16x16x32_bf16 v[56:59], v[168:171], v[212:215], v[56:59]
	v_mfma_f32_16x16x32_bf16 v[48:51], v[160:163], v[220:223], v[48:51]
	v_mfma_f32_16x16x32_bf16 v[40:43], v[168:171], v[220:223], v[40:43]
	v_mfma_f32_16x16x32_bf16 v[32:35], v[160:163], v[228:231], v[32:35]
	v_mfma_f32_16x16x32_bf16 v[24:27], v[168:171], v[228:231], v[24:27]
	v_mfma_f32_16x16x32_bf16 v[16:19], v[160:163], v[236:239], v[16:19]
	v_mfma_f32_16x16x32_bf16 v[8:11], v[168:171], v[236:239], v[8:11]
	s_setprio 0
	s_setprio 1
	v_mfma_f32_16x16x32_bf16 v[60:63], v[172:175], v[208:211], v[60:63]
	v_mfma_f32_16x16x32_bf16 v[52:55], v[180:183], v[208:211], v[52:55]
	v_mfma_f32_16x16x32_bf16 v[44:47], v[172:175], v[216:219], v[44:47]
	v_mfma_f32_16x16x32_bf16 v[36:39], v[180:183], v[216:219], v[36:39]
	v_mfma_f32_16x16x32_bf16 v[28:31], v[172:175], v[224:227], v[28:31]
	v_mfma_f32_16x16x32_bf16 v[20:23], v[180:183], v[224:227], v[20:23]
	v_mfma_f32_16x16x32_bf16 v[12:15], v[172:175], v[232:235], v[12:15]
	v_mfma_f32_16x16x32_bf16 v[4:7], v[180:183], v[232:235], v[4:7]
	v_mfma_f32_16x16x32_bf16 v[60:63], v[176:179], v[212:215], v[60:63]
	v_mfma_f32_16x16x32_bf16 v[52:55], v[184:187], v[212:215], v[52:55]
	v_mfma_f32_16x16x32_bf16 v[44:47], v[176:179], v[220:223], v[44:47]
	v_mfma_f32_16x16x32_bf16 v[36:39], v[184:187], v[220:223], v[36:39]
	v_mfma_f32_16x16x32_bf16 v[28:31], v[176:179], v[228:231], v[28:31]
	v_mfma_f32_16x16x32_bf16 v[20:23], v[184:187], v[228:231], v[20:23]
	v_mfma_f32_16x16x32_bf16 v[12:15], v[176:179], v[236:239], v[12:15]
	v_mfma_f32_16x16x32_bf16 v[4:7], v[184:187], v[236:239], v[4:7]
	s_setprio 0
	s_barrier
	s_add_i32 s46, 0, 0x18000
	s_add_i32 s47, 0, 0x1c000
	v_add_u32_e32 v168, s46, v150
	v_add_u32_e32 v184, s47, v150
	ds_read_b128 v[156:159], v168
	ds_read_b128 v[160:163], v168 offset:1024
	ds_read_b128 v[164:167], v168 offset:2048
	ds_read_b128 v[168:171], v168 offset:3072
	ds_read_b128 v[172:175], v184
	ds_read_b128 v[176:179], v184 offset:1024
	ds_read_b128 v[180:183], v184 offset:2048
	ds_read_b128 v[184:187], v184 offset:3072
	s_add_u32 s18, s24, 0x40000
	s_addc_u32 s19, s25, 0
	s_mov_b32 m0, s48
	ds_read_b128 v[208:211], v155 offset:32768
	ds_read_b128 v[212:215], v155 offset:33792
	ds_read_b128 v[216:219], v155 offset:34816
	ds_read_b128 v[220:223], v155 offset:35840
	ds_read_b128 v[224:227], v155 offset:36864
	ds_read_b128 v[228:231], v155 offset:37888
	ds_read_b128 v[232:235], v155 offset:38912
	ds_read_b128 v[236:239], v155 offset:39936
	global_load_lds_dwordx4 v0, s[18:19]
	s_mov_b32 m0, s49
	s_nop 0
	global_load_lds_dwordx4 v140, s[18:19]
	s_waitcnt vmcnt(8)
	s_waitcnt lgkmcnt(0)
	s_barrier
	s_setprio 1
	s_waitcnt lgkmcnt(0)
	v_mfma_f32_16x16x32_bf16 v[128:131], v[156:159], v[208:211], v[128:131]
	v_mfma_f32_16x16x32_bf16 v[120:123], v[164:167], v[208:211], v[120:123]
	v_mfma_f32_16x16x32_bf16 v[112:115], v[156:159], v[216:219], v[112:115]
	v_mfma_f32_16x16x32_bf16 v[104:107], v[164:167], v[216:219], v[104:107]
	v_mfma_f32_16x16x32_bf16 v[96:99], v[156:159], v[224:227], v[96:99]
	v_mfma_f32_16x16x32_bf16 v[88:91], v[164:167], v[224:227], v[88:91]
	v_mfma_f32_16x16x32_bf16 v[80:83], v[156:159], v[232:235], v[80:83]
	v_mfma_f32_16x16x32_bf16 v[72:75], v[164:167], v[232:235], v[72:75]
	v_mfma_f32_16x16x32_bf16 v[128:131], v[160:163], v[212:215], v[128:131]
	v_mfma_f32_16x16x32_bf16 v[120:123], v[168:171], v[212:215], v[120:123]
	v_mfma_f32_16x16x32_bf16 v[112:115], v[160:163], v[220:223], v[112:115]
	v_mfma_f32_16x16x32_bf16 v[104:107], v[168:171], v[220:223], v[104:107]
	v_mfma_f32_16x16x32_bf16 v[96:99], v[160:163], v[228:231], v[96:99]
	v_mfma_f32_16x16x32_bf16 v[88:91], v[168:171], v[228:231], v[88:91]
	v_mfma_f32_16x16x32_bf16 v[80:83], v[160:163], v[236:239], v[80:83]
	v_mfma_f32_16x16x32_bf16 v[72:75], v[168:171], v[236:239], v[72:75]
	s_setprio 0
	s_setprio 1
	v_mfma_f32_16x16x32_bf16 v[124:127], v[172:175], v[208:211], v[124:127]
	v_mfma_f32_16x16x32_bf16 v[116:119], v[180:183], v[208:211], v[116:119]
	v_mfma_f32_16x16x32_bf16 v[108:111], v[172:175], v[216:219], v[108:111]
	v_mfma_f32_16x16x32_bf16 v[100:103], v[180:183], v[216:219], v[100:103]
	v_mfma_f32_16x16x32_bf16 v[92:95], v[172:175], v[224:227], v[92:95]
	v_mfma_f32_16x16x32_bf16 v[84:87], v[180:183], v[224:227], v[84:87]
	v_mfma_f32_16x16x32_bf16 v[76:79], v[172:175], v[232:235], v[76:79]
	v_mfma_f32_16x16x32_bf16 v[68:71], v[180:183], v[232:235], v[68:71]
	v_mfma_f32_16x16x32_bf16 v[124:127], v[176:179], v[212:215], v[124:127]
	v_mfma_f32_16x16x32_bf16 v[116:119], v[184:187], v[212:215], v[116:119]
	v_mfma_f32_16x16x32_bf16 v[108:111], v[176:179], v[220:223], v[108:111]
	v_mfma_f32_16x16x32_bf16 v[100:103], v[184:187], v[220:223], v[100:103]
	v_mfma_f32_16x16x32_bf16 v[92:95], v[176:179], v[228:231], v[92:95]
	v_mfma_f32_16x16x32_bf16 v[84:87], v[184:187], v[228:231], v[84:87]
	v_mfma_f32_16x16x32_bf16 v[76:79], v[176:179], v[236:239], v[76:79]
	v_mfma_f32_16x16x32_bf16 v[68:71], v[184:187], v[236:239], v[68:71]
	s_setprio 0
	s_barrier
	s_add_i32 s18, s46, s28
	s_add_u32 s100, s22, 0x80
	s_addc_u32 s101, s23, 0
	s_mov_b32 m0, s18
	ds_read_b128 v[208:211], v155 offset:49152
	ds_read_b128 v[212:215], v155 offset:50176
	ds_read_b128 v[216:219], v155 offset:51200
	ds_read_b128 v[220:223], v155 offset:52224
	ds_read_b128 v[224:227], v155 offset:53248
	ds_read_b128 v[228:231], v155 offset:54272
	ds_read_b128 v[232:235], v155 offset:55296
	ds_read_b128 v[236:239], v155 offset:56320
	global_load_lds_dwordx4 v2, s[100:101]
	s_add_i32 m0, s18, 0x2000
	s_add_u32 s18, s22, 0x40080
	s_addc_u32 s19, s23, 0
	s_add_i32 s22, s47, s28
	global_load_lds_dwordx4 v142, s[100:101]
	s_mov_b32 m0, s22
	s_nop 0
	global_load_lds_dwordx4 v2, s[18:19]
	s_add_i32 m0, s22, 0x2000
	s_nop 0
	global_load_lds_dwordx4 v142, s[18:19]
	s_add_u32 s100, s24, 0x80
	s_addc_u32 s101, s25, 0
	s_mov_b32 m0, s50
	s_nop 0
	global_load_lds_dwordx4 v0, s[100:101]
	s_mov_b32 m0, s51
	s_nop 0
	global_load_lds_dwordx4 v140, s[100:101]
	s_waitcnt vmcnt(8)
	s_waitcnt lgkmcnt(0)
	s_barrier
	s_setprio 1
	s_waitcnt lgkmcnt(0)
	v_mfma_f32_16x16x32_bf16 v[64:67], v[156:159], v[208:211], v[64:67]
	v_mfma_f32_16x16x32_bf16 v[56:59], v[164:167], v[208:211], v[56:59]
	v_mfma_f32_16x16x32_bf16 v[48:51], v[156:159], v[216:219], v[48:51]
	v_mfma_f32_16x16x32_bf16 v[40:43], v[164:167], v[216:219], v[40:43]
	v_mfma_f32_16x16x32_bf16 v[32:35], v[156:159], v[224:227], v[32:35]
	v_mfma_f32_16x16x32_bf16 v[24:27], v[164:167], v[224:227], v[24:27]
	v_mfma_f32_16x16x32_bf16 v[16:19], v[156:159], v[232:235], v[16:19]
	v_mfma_f32_16x16x32_bf16 v[8:11], v[164:167], v[232:235], v[8:11]
	v_mfma_f32_16x16x32_bf16 v[64:67], v[160:163], v[212:215], v[64:67]
	v_mfma_f32_16x16x32_bf16 v[56:59], v[168:171], v[212:215], v[56:59]
	v_mfma_f32_16x16x32_bf16 v[48:51], v[160:163], v[220:223], v[48:51]
	v_mfma_f32_16x16x32_bf16 v[40:43], v[168:171], v[220:223], v[40:43]
	v_mfma_f32_16x16x32_bf16 v[32:35], v[160:163], v[228:231], v[32:35]
	v_mfma_f32_16x16x32_bf16 v[24:27], v[168:171], v[228:231], v[24:27]
	v_mfma_f32_16x16x32_bf16 v[16:19], v[160:163], v[236:239], v[16:19]
	v_mfma_f32_16x16x32_bf16 v[8:11], v[168:171], v[236:239], v[8:11]
	s_setprio 0
	s_setprio 1
	v_mfma_f32_16x16x32_bf16 v[60:63], v[172:175], v[208:211], v[60:63]
	v_mfma_f32_16x16x32_bf16 v[52:55], v[180:183], v[208:211], v[52:55]
	v_mfma_f32_16x16x32_bf16 v[44:47], v[172:175], v[216:219], v[44:47]
	v_mfma_f32_16x16x32_bf16 v[36:39], v[180:183], v[216:219], v[36:39]
	v_mfma_f32_16x16x32_bf16 v[28:31], v[172:175], v[224:227], v[28:31]
	v_mfma_f32_16x16x32_bf16 v[20:23], v[180:183], v[224:227], v[20:23]
	v_mfma_f32_16x16x32_bf16 v[12:15], v[172:175], v[232:235], v[12:15]
	v_mfma_f32_16x16x32_bf16 v[4:7], v[180:183], v[232:235], v[4:7]
	v_mfma_f32_16x16x32_bf16 v[60:63], v[176:179], v[212:215], v[60:63]
	v_mfma_f32_16x16x32_bf16 v[52:55], v[184:187], v[212:215], v[52:55]
	v_mfma_f32_16x16x32_bf16 v[44:47], v[176:179], v[220:223], v[44:47]
	v_mfma_f32_16x16x32_bf16 v[36:39], v[184:187], v[220:223], v[36:39]
	v_mfma_f32_16x16x32_bf16 v[28:31], v[176:179], v[228:231], v[28:31]
	v_mfma_f32_16x16x32_bf16 v[20:23], v[184:187], v[228:231], v[20:23]
	v_mfma_f32_16x16x32_bf16 v[12:15], v[176:179], v[236:239], v[12:15]
	v_mfma_f32_16x16x32_bf16 v[4:7], v[184:187], v[236:239], v[4:7]
	s_setprio 0
	s_barrier
	s_add_i32 s15, s15, 2
	s_add_u32 s44, s44, 0x100
	s_addc_u32 s45, s45, 0
	s_add_u32 s13, s13, 0x100
	s_addc_u32 s14, s14, 0
	s_cmp_gt_u32 s15, 13
	s_cbranch_scc0 .LBB0_98
	s_lshl_b32 s5, s42, 8
	s_and_b64 vcc, exec, s[2:3]
	s_cbranch_vccz .LBB0_101
	v_or_b32_e32 v148, s5, v152
	v_ashrrev_i32_e32 v149, 31, v148
	v_readlane_b32 s10, v255, 11
	v_lshlrev_b64 v[148:149], 6, v[148:149]
	v_readlane_b32 s11, v255, 12
	s_nop 1
	v_lshl_add_u64 v[148:149], s[10:11], 0, v[148:149]
	global_load_dwordx4 v[156:159], v[148:149], off
	global_load_dwordx4 v[160:163], v[148:149], off offset:32
	global_load_dwordx4 v[164:167], v[148:149], off offset:16
	global_load_dwordx4 v[168:171], v[148:149], off offset:48
	s_barrier
